# attention: finalize split across two steps (normalisation, scale multiplies and bf16 packs at the end of the job's last step behind its PV MFMAs; lane swaps and stores in the next step)
# speedup vs baseline: 1.0004x; 1.0002x over previous
; __device__ __forceinline__ void attn_chain(LAS unsigned char* lds, const bf16* Qb, const bf16* Kb, const bf16* Vb, bf16* Ob, float* lseb, int g0, int wave, int lane) {
;     ...
;     for (int s = 0; s < NSTEP; ++s) {
;         const int rel = s - cw; const bool act = rel >= 0 && rel < 5 * NJOB;
;         const int n = act ? rel / 5 : 0, t = act ? rel - 5 * n : 3;
.LBB0_642:
	s_cmp_lt_u32 s84, 30
	s_cbranch_scc0 .Lattn_nosplit
	s_cmp_eq_u32 s15, 4
	s_cbranch_scc0 .Lattn_nosplit
	s_cmp_lt_u32 s14, 5
	s_cbranch_scc0 .Lattn_nosplit
	v_mov_b32_e32 v246, v182
	v_mov_b32_e32 v247, v182
	s_nop 1
	v_permlane32_swap_b32_e32 v246, v247
	s_nop 1
	v_add_f32_e32 v245, v247, v246
	v_div_scale_f32 v248, s[90:91], v245, v245, 1.0
	v_rcp_f32_e32 v249, v248
	s_nop 1
	v_fma_f32 v250, -v248, v249, 1.0
	v_fmac_f32_e32 v249, v250, v249
	v_div_scale_f32 v250, vcc, 1.0, v245, 1.0
	v_mul_f32_e32 v251, v250, v249
	v_fma_f32 v252, -v248, v251, v250
	v_fmac_f32_e32 v251, v252, v249
	v_fma_f32 v248, -v248, v251, v250
	v_div_fmas_f32 v248, v248, v249, v251
	v_div_fixup_f32 v244, v248, v245, 1.0
	s_nop 7
	s_nop 7
	v_pk_mul_f32 v[0:1], v[0:1], v[244:245] op_sel_hi:[1,0]
	v_pk_mul_f32 v[2:3], v[2:3], v[244:245] op_sel_hi:[1,0]
	v_pk_mul_f32 v[4:5], v[4:5], v[244:245] op_sel_hi:[1,0]
	v_pk_mul_f32 v[6:7], v[6:7], v[244:245] op_sel_hi:[1,0]
	v_pk_mul_f32 v[8:9], v[8:9], v[244:245] op_sel_hi:[1,0]
	v_pk_mul_f32 v[10:11], v[10:11], v[244:245] op_sel_hi:[1,0]
	v_pk_mul_f32 v[12:13], v[12:13], v[244:245] op_sel_hi:[1,0]
	v_pk_mul_f32 v[14:15], v[14:15], v[244:245] op_sel_hi:[1,0]
	v_pk_mul_f32 v[16:17], v[16:17], v[244:245] op_sel_hi:[1,0]
	v_pk_mul_f32 v[18:19], v[18:19], v[244:245] op_sel_hi:[1,0]
	v_pk_mul_f32 v[20:21], v[20:21], v[244:245] op_sel_hi:[1,0]
	v_pk_mul_f32 v[22:23], v[22:23], v[244:245] op_sel_hi:[1,0]
	v_pk_mul_f32 v[24:25], v[24:25], v[244:245] op_sel_hi:[1,0]
	v_pk_mul_f32 v[26:27], v[26:27], v[244:245] op_sel_hi:[1,0]
	v_pk_mul_f32 v[28:29], v[28:29], v[244:245] op_sel_hi:[1,0]
	v_pk_mul_f32 v[30:31], v[30:31], v[244:245] op_sel_hi:[1,0]
	v_pk_mul_f32 v[32:33], v[32:33], v[244:245] op_sel_hi:[1,0]
	v_pk_mul_f32 v[34:35], v[34:35], v[244:245] op_sel_hi:[1,0]
	v_pk_mul_f32 v[36:37], v[36:37], v[244:245] op_sel_hi:[1,0]
	v_pk_mul_f32 v[38:39], v[38:39], v[244:245] op_sel_hi:[1,0]
	v_pk_mul_f32 v[40:41], v[40:41], v[244:245] op_sel_hi:[1,0]
	v_pk_mul_f32 v[42:43], v[42:43], v[244:245] op_sel_hi:[1,0]
	v_pk_mul_f32 v[44:45], v[44:45], v[244:245] op_sel_hi:[1,0]
	v_pk_mul_f32 v[46:47], v[46:47], v[244:245] op_sel_hi:[1,0]
	v_pk_mul_f32 v[48:49], v[48:49], v[244:245] op_sel_hi:[1,0]
	v_pk_mul_f32 v[50:51], v[50:51], v[244:245] op_sel_hi:[1,0]
	v_pk_mul_f32 v[52:53], v[52:53], v[244:245] op_sel_hi:[1,0]
	v_pk_mul_f32 v[54:55], v[54:55], v[244:245] op_sel_hi:[1,0]
	v_pk_mul_f32 v[56:57], v[56:57], v[244:245] op_sel_hi:[1,0]
	v_pk_mul_f32 v[58:59], v[58:59], v[244:245] op_sel_hi:[1,0]
	v_pk_mul_f32 v[60:61], v[60:61], v[244:245] op_sel_hi:[1,0]
	v_pk_mul_f32 v[62:63], v[62:63], v[244:245] op_sel_hi:[1,0]
	v_cvt_pk_bf16_f32 v48, v48, v49
	v_cvt_pk_bf16_f32 v49, v50, v51
	v_cvt_pk_bf16_f32 v50, v52, v53
	v_cvt_pk_bf16_f32 v51, v54, v55
	v_cvt_pk_bf16_f32 v56, v56, v57
	v_cvt_pk_bf16_f32 v57, v58, v59
	v_cvt_pk_bf16_f32 v58, v60, v61
	v_cvt_pk_bf16_f32 v59, v62, v63
	v_cvt_pk_bf16_f32 v32, v32, v33
	v_cvt_pk_bf16_f32 v33, v34, v35
	v_cvt_pk_bf16_f32 v34, v36, v37
	v_cvt_pk_bf16_f32 v35, v38, v39
	v_cvt_pk_bf16_f32 v40, v40, v41
	v_cvt_pk_bf16_f32 v41, v42, v43
	v_cvt_pk_bf16_f32 v42, v44, v45
	v_cvt_pk_bf16_f32 v43, v46, v47
	v_cvt_pk_bf16_f32 v16, v16, v17
	v_cvt_pk_bf16_f32 v17, v18, v19
	v_cvt_pk_bf16_f32 v18, v20, v21
	v_cvt_pk_bf16_f32 v19, v22, v23
	v_cvt_pk_bf16_f32 v24, v24, v25
	v_cvt_pk_bf16_f32 v25, v26, v27
	v_cvt_pk_bf16_f32 v26, v28, v29
	v_cvt_pk_bf16_f32 v27, v30, v31
	v_cvt_pk_bf16_f32 v0, v0, v1
	v_cvt_pk_bf16_f32 v1, v2, v3
	v_cvt_pk_bf16_f32 v2, v4, v5
	v_cvt_pk_bf16_f32 v3, v6, v7
	v_cvt_pk_bf16_f32 v8, v8, v9
	v_cvt_pk_bf16_f32 v9, v10, v11
	v_cvt_pk_bf16_f32 v10, v12, v13
	v_cvt_pk_bf16_f32 v11, v14, v15

.Lattn_q_done:
.LBB0_691:
	s_andn2_b64 vcc, exec, s[6:7]
	s_cbranch_vccnz .LBB0_642
	s_and_b64 s[6:7], s[70:71], s[72:73]
	s_andn2_b64 vcc, exec, s[6:7]
	s_lshl_b32 s2, s2, 3
	s_cbranch_vccnz .LBB0_696
	s_add_i32 s3, s80, s2
	s_ashr_i32 s6, s3, 7
	s_lshl_b32 s7, s6, 1
	s_sub_i32 s12, 7, s7
	s_and_b32 s13, s3, 0x7f
	s_lshr_b32 s31, s13, s12
	s_lshl_b32 s12, -1, s12
	s_andn2_b32 s3, s3, s12
	v_lshl_or_b32 v64, s3, 5, v157
	v_lshlrev_b32_e32 v64, s7, v64
	s_ashr_i32 s7, s6, 31
	v_add_u32_e32 v64, s31, v64
	v_mov_b32_e32 v66, v245
	s_lshl_b64 s[12:13], s[6:7], 25
	s_add_u32 s12, s28, s12
	v_ashrrev_i32_e32 v65, 31, v64
	s_addc_u32 s13, s57, s13
	v_lshlrev_b64 v[70:71], 11, v[64:65]
	v_lshl_add_u64 v[70:71], s[12:13], 0, v[70:71]
	v_lshl_add_u64 v[70:71], v[144:145], 1, v[70:71]
	v_permlane32_swap_b32_e32 v48, v50
	v_permlane32_swap_b32_e32 v49, v51
	v_permlane32_swap_b32_e32 v32, v34
	v_permlane32_swap_b32_e32 v33, v35
	v_permlane32_swap_b32_e32 v16, v18
	v_permlane32_swap_b32_e32 v17, v19
	v_permlane32_swap_b32_e32 v0, v2
	v_permlane32_swap_b32_e32 v1, v3
	global_store_dwordx4 v[70:71], v[48:51], off
	global_store_dwordx4 v[70:71], v[32:35], off offset:64
	global_store_dwordx4 v[70:71], v[16:19], off offset:128
	global_store_dwordx4 v[70:71], v[0:3], off offset:192
	v_permlane32_swap_b32_e32 v56, v58
	v_permlane32_swap_b32_e32 v57, v59
	v_permlane32_swap_b32_e32 v40, v42
	v_permlane32_swap_b32_e32 v41, v43
	v_permlane32_swap_b32_e32 v24, v26
	v_permlane32_swap_b32_e32 v25, v27
	v_permlane32_swap_b32_e32 v8, v10
	v_permlane32_swap_b32_e32 v9, v11
	global_store_dwordx4 v[70:71], v[56:59], off offset:32
	global_store_dwordx4 v[70:71], v[40:43], off offset:96
	global_store_dwordx4 v[70:71], v[24:27], off offset:160
	global_store_dwordx4 v[70:71], v[8:11], off offset:224
	s_and_saveexec_b64 s[70:71], s[4:5]
	s_cbranch_execz .LBB0_695
	v_cmp_gt_f32_e32 vcc, s93, v66
	s_lshl_b64 s[6:7], s[6:7], 19
	s_add_u32 s6, s22, s6
	v_cndmask_b32_e64 v0, 0, 32, vcc
	v_ldexp_f32 v0, v66, v0
	v_log_f32_e32 v2, v0
	v_cndmask_b32_e32 v3, 0, v236, vcc
	s_addc_u32 s7, s23, s7
	v_lshlrev_b64 v[0:1], 5, v[64:65]
	v_sub_f32_e32 v2, v2, v3
	v_lshl_add_u64 v[0:1], s[6:7], 0, v[0:1]
	v_add_f32_e32 v2, v149, v2
	global_store_dword v[0:1], v2, off
